# gdn_pre next-unit scalar prologue: dt_bias/a_log loads issued at its top instead of behind two waits
# speedup vs baseline: 1.0064x; 1.0064x over previous
.LBB0_304:
	s_cmpk_eq_i32 s85, 0x200
	s_cselect_b64 s[8:9], -1, 0
	s_or_b64 s[8:9], s[30:31], s[8:9]
	s_and_b64 vcc, exec, s[8:9]
	s_waitcnt lgkmcnt(0)
	s_barrier
	s_cbranch_vccnz .LBB0_226
	v_readlane_b32 s8, v241, 19
	v_readlane_b32 s9, v241, 20
	v_readlane_b32 s44, v241, 21
	v_readlane_b32 s45, v241, 22
	s_nop 4
	global_load_dword v222, v85, s[8:9]
	global_load_dword v223, v85, s[44:45]
	s_and_b32 s8, s84, 0xfffff800
	s_lshl_b32 s9, s84, 3
	s_and_b32 s9, s9, 0x7c0
	s_or_b32 s8, s8, s9
	v_mbcnt_lo_u32_b32 v0, -1, 0
	v_mbcnt_hi_u32_b32 v0, -1, v0
	s_mov_b32 s42, 0xbfb8aa3b
	v_add_u32_e32 v2, s8, v0
	v_ashrrev_i32_e32 v3, 31, v2
	v_readlane_b32 s8, v241, 17
	v_lshlrev_b64 v[2:3], 6, v[2:3]
	v_readlane_b32 s9, v241, 18
	s_mov_b32 s43, 0x42ce8ed0
	s_mov_b32 s44, 0xc2b17218
	v_lshl_add_u64 v[2:3], s[8:9], 0, v[2:3]
	global_load_dword v1, v[2:3], off
	s_nop 0
	global_load_dword v2, v[2:3], off offset:32
	v_readlane_b32 s8, v241, 19
	v_readlane_b32 s9, v241, 20
	s_waitcnt vmcnt(1)
	v_mul_f32_e32 v3, 0xbfb8aa3b, v1
	v_fma_f32 v4, v1, s42, -v3
	v_rndne_f32_e32 v5, v3
	v_fmac_f32_e32 v4, 0xb2a5705f, v1
	v_sub_f32_e32 v3, v3, v5
	v_add_f32_e32 v3, v3, v4
	v_exp_f32_e32 v3, v3
	v_cvt_i32_f32_e32 v4, v5
	v_cmp_nlt_f32_e32 vcc, s43, v1
	v_ldexp_f32 v3, v3, v4
	s_nop 0
	v_cndmask_b32_e32 v3, 0, v3, vcc
	v_cmp_ngt_f32_e32 vcc, s44, v1
	s_nop 1
	v_cndmask_b32_e32 v1, v150, v3, vcc
	v_mov_b32_e32 v3, v222
	s_mov_b32 s8, 0xb2a5705f
	v_add_f32_e32 v1, 1.0, v1
	s_waitcnt vmcnt(0)
	v_add_f32_e32 v2, v2, v3
	v_mul_f32_e64 v3, |v2|, s42
	v_fma_f32 v5, |v2|, s42, -v3
	v_rndne_f32_e32 v6, v3
	v_fma_f32 v5, |v2|, s8, v5
	v_sub_f32_e32 v3, v3, v6
	v_add_f32_e32 v3, v3, v5
	v_exp_f32_e32 v3, v3
	v_cvt_i32_f32_e32 v5, v6
	v_cmp_ngt_f32_e64 vcc, |v2|, s43
	v_max_f32_e32 v4, 0, v2
	s_mov_b32 s8, 0x3f2aaaab
	v_ldexp_f32 v3, v3, v5
	v_cndmask_b32_e32 v3, 0, v3, vcc
	v_cmp_nlt_f32_e64 vcc, |v2|, s44
	s_nop 1
	v_cndmask_b32_e32 v5, v150, v3, vcc
	v_add_f32_e32 v6, 1.0, v5
	v_add_f32_e32 v2, -1.0, v6
	v_sub_f32_e32 v3, v2, v6
	v_add_f32_e32 v3, 1.0, v3
	v_sub_f32_e32 v2, v5, v2
	v_add_f32_e32 v7, v2, v3
	v_frexp_mant_f32_e32 v2, v6
	v_cmp_gt_f32_e32 vcc, s8, v2
	v_cvt_f64_f32_e32 v[2:3], v6
	v_frexp_exp_i32_f64_e32 v2, v[2:3]
	v_subbrev_co_u32_e32 v2, vcc, 0, v2, vcc
	v_sub_u32_e32 v3, 0, v2
	v_ldexp_f32 v6, v6, v3
	v_ldexp_f32 v3, v7, v3
	v_add_f32_e32 v7, -1.0, v6
	v_add_f32_e32 v8, 1.0, v7
	v_sub_f32_e32 v8, v6, v8
	v_add_f32_e32 v8, v3, v8
	v_add_f32_e32 v9, v7, v8
	v_sub_f32_e32 v7, v7, v9
	v_add_f32_e32 v7, v8, v7
	v_add_f32_e32 v8, 1.0, v6
	v_add_f32_e32 v10, -1.0, v8
	v_sub_f32_e32 v6, v6, v10
	v_add_f32_e32 v3, v3, v6
	v_add_f32_e32 v6, v8, v3
	v_sub_f32_e32 v8, v8, v6
	v_add_f32_e32 v3, v3, v8
	v_rcp_f32_e32 v8, v6
	v_cvt_f32_i32_e32 v2, v2
	s_mov_b32 s8, 0x3f317218
	v_mul_f32_e32 v10, v9, v8
	v_mul_f32_e32 v11, v6, v10
	v_fma_f32 v12, v10, v6, -v11
	v_fmac_f32_e32 v12, v10, v3
	v_add_f32_e32 v13, v11, v12
	v_sub_f32_e32 v14, v9, v13
	v_sub_f32_e32 v9, v9, v14
	v_sub_f32_e32 v11, v13, v11
	v_sub_f32_e32 v9, v9, v13
	v_add_f32_e32 v7, v7, v9
	v_sub_f32_e32 v9, v11, v12
	v_add_f32_e32 v7, v9, v7
	v_add_f32_e32 v9, v14, v7
	v_mul_f32_e32 v11, v8, v9
	v_mul_f32_e32 v12, v6, v11
	v_fma_f32 v6, v11, v6, -v12
	v_fmac_f32_e32 v6, v11, v3
	v_sub_f32_e32 v3, v14, v9
	v_add_f32_e32 v3, v7, v3
	v_add_f32_e32 v7, v12, v6
	v_sub_f32_e32 v13, v9, v7
	v_sub_f32_e32 v9, v9, v13
	v_sub_f32_e32 v12, v7, v12
	v_sub_f32_e32 v7, v9, v7
	v_add_f32_e32 v3, v3, v7
	v_sub_f32_e32 v6, v12, v6
	v_add_f32_e32 v3, v6, v3
	v_add_f32_e32 v6, v10, v11
	v_add_f32_e32 v3, v13, v3
	v_sub_f32_e32 v7, v6, v10
	v_mul_f32_e32 v3, v8, v3
	v_sub_f32_e32 v7, v11, v7
	v_add_f32_e32 v3, v7, v3
	v_mul_f32_e32 v10, 0x3f317218, v2
	v_add_f32_e32 v7, v6, v3
	v_fma_f32 v11, v2, s8, -v10
	v_mul_f32_e32 v8, v7, v7
	v_fmac_f32_e32 v11, 0xb102e308, v2
	v_sub_f32_e32 v2, v7, v6
	v_fmamk_f32 v9, v8, 0x3e9b6dac, v147
	v_sub_f32_e32 v2, v3, v2
	v_add_f32_e32 v3, v10, v11
	v_fmaak_f32 v9, v8, v9, 0x3f2aaada
	v_sub_f32_e32 v6, v3, v10
	v_ldexp_f32 v10, v7, 1
	v_mul_f32_e32 v7, v7, v8
	v_mul_f32_e32 v7, v7, v9
	v_add_f32_e32 v8, v10, v7
	v_sub_f32_e32 v9, v8, v10
	v_ldexp_f32 v2, v2, 1
	v_sub_f32_e32 v7, v7, v9
	v_add_f32_e32 v2, v2, v7
	v_add_f32_e32 v7, v8, v2
	v_sub_f32_e32 v8, v7, v8
	v_sub_f32_e32 v2, v2, v8
	v_add_f32_e32 v8, v3, v7
	v_sub_f32_e32 v9, v8, v3
	v_sub_f32_e32 v10, v8, v9
	v_sub_f32_e32 v6, v11, v6
	v_sub_f32_e32 v3, v3, v10
	v_sub_f32_e32 v7, v7, v9
	v_add_f32_e32 v3, v7, v3
	v_add_f32_e32 v7, v6, v2
	v_sub_f32_e32 v9, v7, v6
	v_sub_f32_e32 v10, v7, v9
	v_sub_f32_e32 v6, v6, v10
	v_sub_f32_e32 v2, v2, v9
	v_add_f32_e32 v3, v7, v3
	v_add_f32_e32 v2, v2, v6
	v_add_f32_e32 v6, v8, v3
	v_sub_f32_e32 v7, v6, v8
	v_sub_f32_e32 v3, v3, v7
	v_add_f32_e32 v2, v2, v3
	s_mov_b32 s8, 0x7f800000
	v_add_f32_e32 v2, v6, v2
	v_cmp_neq_f32_e32 vcc, s8, v5
	s_mov_b32 s8, 0x33800000
	s_nop 0
	v_cndmask_b32_e32 v2, v150, v2, vcc
	v_cmp_lt_f32_e64 vcc, |v5|, s8
	v_readlane_b32 s8, v241, 21
	v_readlane_b32 s9, v241, 22
	v_cndmask_b32_e32 v2, v2, v5, vcc
	v_add_f32_e32 v2, v4, v2
	s_nop 2
	v_mov_b32_e32 v3, v223
	s_mov_b32 s8, 0x3fb8aa3b
	s_waitcnt vmcnt(0)
	v_mul_f32_e32 v4, 0x3fb8aa3b, v3
	v_fma_f32 v5, v3, s8, -v4
	v_rndne_f32_e32 v6, v4
	v_fmac_f32_e32 v5, 0x32a5705f, v3
	v_sub_f32_e32 v4, v4, v6
	v_add_f32_e32 v4, v4, v5
	v_exp_f32_e32 v4, v4
	v_cvt_i32_f32_e32 v5, v6
	s_mov_b32 s8, 0xc2ce8ed0
	v_cmp_ngt_f32_e32 vcc, s8, v3
	s_mov_b32 s8, 0x42b17218
	v_ldexp_f32 v4, v4, v5
	v_cndmask_b32_e32 v4, 0, v4, vcc
	v_cmp_nlt_f32_e32 vcc, s8, v3
	v_add_u32_e32 v5, -1, v159
	s_nop 0
	v_cndmask_b32_e32 v3, v150, v4, vcc
	v_cmp_lt_i32_e32 vcc, v5, v97
	v_mul_f32_e64 v4, v2, -v3
	s_nop 0
	v_cndmask_b32_e32 v5, v5, v159, vcc
	v_lshlrev_b32_e32 v5, 2, v5
	ds_bpermute_b32 v5, v5, v4
	v_cmp_gt_i32_e32 vcc, 1, v0
	s_waitcnt lgkmcnt(0)
	v_fma_f32 v2, v2, -v3, v5
	v_add_u32_e32 v3, -2, v159
	v_cndmask_b32_e32 v2, v2, v4, vcc
	v_cmp_lt_i32_e32 vcc, v3, v97
	v_div_scale_f32 v4, s[8:9], v1, v1, 1.0
	s_nop 0
	v_cndmask_b32_e32 v3, v3, v159, vcc
	v_lshlrev_b32_e32 v3, 2, v3
	ds_bpermute_b32 v3, v3, v2
	v_cmp_gt_i32_e32 vcc, 2, v0
	v_rcp_f32_e32 v5, v4
	s_and_b32 s8, s85, 0x80
	s_lshl_b32 s8, s8, 2
	s_waitcnt lgkmcnt(0)
	v_add_f32_e32 v3, v2, v3
	v_cndmask_b32_e32 v2, v3, v2, vcc
	v_add_u32_e32 v3, -4, v159
	v_cmp_lt_i32_e32 vcc, v3, v97
	v_fma_f32 v6, -v4, v5, 1.0
	v_fmac_f32_e32 v5, v6, v5
	v_cndmask_b32_e32 v3, v3, v159, vcc
	v_lshlrev_b32_e32 v3, 2, v3
	ds_bpermute_b32 v3, v3, v2
	v_cmp_gt_i32_e32 vcc, 4, v0
	s_add_i32 s8, s18, s8
	s_waitcnt lgkmcnt(0)
	v_add_f32_e32 v3, v2, v3
	v_cndmask_b32_e32 v2, v3, v2, vcc
	v_add_u32_e32 v3, -8, v159
	v_cmp_lt_i32_e32 vcc, v3, v97
	s_nop 1
	v_cndmask_b32_e32 v3, v3, v159, vcc
	v_lshlrev_b32_e32 v3, 2, v3
	ds_bpermute_b32 v3, v3, v2
	v_cmp_gt_i32_e32 vcc, 8, v0
	s_waitcnt lgkmcnt(0)
	v_add_f32_e32 v3, v2, v3
	v_cndmask_b32_e32 v2, v3, v2, vcc
	v_add_u32_e32 v3, -16, v159
	v_cmp_lt_i32_e32 vcc, v3, v97
	s_nop 1
	v_cndmask_b32_e32 v3, v3, v159, vcc
	v_lshlrev_b32_e32 v3, 2, v3
	ds_bpermute_b32 v3, v3, v2
	v_cmp_gt_i32_e32 vcc, 16, v0
	s_waitcnt lgkmcnt(0)
	v_add_f32_e32 v3, v2, v3
	v_cndmask_b32_e32 v3, v3, v2, vcc
	v_subrev_u32_e32 v2, 32, v159
	v_cmp_lt_i32_e32 vcc, v2, v97
	s_nop 1
	v_cndmask_b32_e32 v2, v2, v159, vcc
	v_lshlrev_b32_e32 v2, 2, v2
	ds_bpermute_b32 v2, v2, v3
	v_cmp_gt_i32_e32 vcc, 32, v0
	s_waitcnt lgkmcnt(0)
	v_add_f32_e32 v2, v3, v2
	v_cndmask_b32_e32 v3, v2, v3, vcc
	v_div_scale_f32 v6, vcc, 1.0, v1, 1.0
	v_mul_f32_e32 v7, v6, v5
	v_fma_f32 v8, -v4, v7, v6
	v_fmac_f32_e32 v7, v8, v5
	v_fma_f32 v4, -v4, v7, v6
	v_div_fmas_f32 v4, v4, v5, v7
	v_div_fixup_f32 v1, v4, v1, 1.0
	v_lshl_add_u32 v4, v0, 2, s8
	v_cmp_eq_u32_e32 vcc, 63, v0
	ds_write2st64_b32 v4, v3, v1 offset1:1
	s_and_saveexec_b64 s[8:9], vcc
	s_cbranch_execz .LBB0_225
	v_mul_f32_e32 v0, 0x3fb8aa3b, v2
	v_rndne_f32_e32 v1, v0
	s_mov_b32 s42, 0x3fb8aa3b
	v_sub_f32_e32 v3, v0, v1
	v_fma_f32 v0, v2, s42, -v0
	v_fmac_f32_e32 v0, 0x32a5705f, v2
	v_add_f32_e32 v0, v3, v0
	v_exp_f32_e32 v0, v0
	v_cvt_i32_f32_e32 v1, v1
	s_mov_b32 s43, 0xc2ce8ed0
	s_add_i32 s42, s72, 8
	v_cmp_ngt_f32_e32 vcc, s43, v2
	v_ldexp_f32 v0, v0, v1
	s_mov_b32 s43, 0x42b17218
	v_cndmask_b32_e32 v0, 0, v0, vcc
	v_cmp_nlt_f32_e32 vcc, s43, v2
	s_ashr_i32 s43, s42, 31
	s_lshl_b64 s[42:43], s[42:43], 2
	v_readlane_b32 s44, v241, 7
	v_readlane_b32 s45, v241, 8
	s_add_u32 s42, s44, s42
	v_cndmask_b32_e32 v0, v150, v0, vcc
	s_addc_u32 s43, s45, s43
	global_store_dword v85, v0, s[42:43]
	s_branch .LBB0_225
